# gates->merge barrier: B-finalize Y stores write-through (sc1), XCD leader skips the L2 write-back (G and M/H never leave their XCD)
# speedup vs baseline: 1.0027x; 1.0027x over previous
.LBB0_591:
	s_or_b64 exec, exec, s[18:19]
	s_waitcnt vmcnt(4)
	v_max3_f32 v65, v89, v88, v87
	v_sub_f32_e32 v74, v89, v65
	v_mul_f32_e32 v74, 0x3fb8aa3b, v74
	v_exp_f32_e32 v75, v74
	v_sub_f32_e32 v74, v88, v65
	v_mul_f32_e32 v74, 0x3fb8aa3b, v74
	v_sub_f32_e32 v65, v87, v65
	v_exp_f32_e32 v74, v74
	v_mul_f32_e32 v65, 0x3fb8aa3b, v65
	s_waitcnt vmcnt(0)
	v_lshlrev_b32_e32 v88, 16, v60
	v_exp_f32_e32 v65, v65
	v_mul_f32_e32 v87, 0xbfb8aa3b, v88
	v_exp_f32_e32 v87, v87
	v_add_f32_e32 v89, v75, v74
	v_and_b32_e32 v94, 0xffff0000, v60
	v_add_f32_e32 v89, v65, v89
	v_mul_f32_e32 v60, 0xbfb8aa3b, v94
	v_rcp_f32_e32 v90, v89
	v_add_f32_e32 v87, 1.0, v87
	v_exp_f32_e32 v60, v60
	v_rcp_f32_e32 v92, v87
	v_mul_f32_e32 v93, v65, v90
	v_lshlrev_b32_e32 v89, 16, v56
	v_add_f32_e32 v60, 1.0, v60
	v_pk_mul_f32 v[88:89], v[92:93], v[88:89]
	v_rcp_f32_e32 v92, v60
	v_lshlrev_b32_e32 v60, 16, v61
	v_mul_f32_e32 v65, 0xbfb8aa3b, v60
	v_exp_f32_e32 v65, v65
	v_and_b32_e32 v95, 0xffff0000, v56
	v_pk_mul_f32 v[94:95], v[92:93], v[94:95]
	v_pk_mul_f32 v[74:75], v[74:75], v[90:91] op_sel_hi:[1,0]
	v_add_f32_e32 v56, 1.0, v65
	v_rcp_f32_e32 v92, v56
	v_and_b32_e32 v56, 0xffff0000, v61
	v_mul_f32_e32 v61, 0xbfb8aa3b, v56
	v_exp_f32_e32 v65, v61
	v_lshlrev_b32_e32 v91, 16, v48
	v_lshlrev_b32_e32 v90, 16, v52
	v_pk_mul_f32 v[90:91], v[74:75], v[90:91]
	v_lshlrev_b32_e32 v97, 16, v58
	v_and_b32_e32 v99, 0xffff0000, v58
	v_add_f32_e32 v58, v90, v91
	v_lshlrev_b32_e32 v61, 16, v57
	v_add_f32_e32 v65, 1.0, v65
	v_lshlrev_b32_e32 v96, 16, v62
	v_add_f32_e32 v58, v89, v58
	v_pk_mul_f32 v[60:61], v[92:93], v[60:61]
	v_rcp_f32_e32 v92, v65
	v_mul_f32_e32 v65, 0xbfb8aa3b, v96
	v_mul_f32_e32 v58, v88, v58
	v_and_b32_e32 v89, 0xffff0000, v48
	v_and_b32_e32 v88, 0xffff0000, v52
	v_exp_f32_e32 v65, v65
	v_pk_mul_f32 v[88:89], v[74:75], v[88:89]
	v_and_b32_e32 v57, 0xffff0000, v57
	v_add_f32_e32 v48, v88, v89
	v_lshlrev_b32_e32 v89, 16, v49
	v_lshlrev_b32_e32 v88, 16, v53
	v_pk_mul_f32 v[88:89], v[74:75], v[88:89]
	v_add_f32_e32 v48, v95, v48
	v_add_f32_e32 v52, v88, v89
	v_add_f32_e32 v65, 1.0, v65
	v_mul_f32_e32 v48, v94, v48
	v_add_f32_e32 v52, v61, v52
	v_pk_mul_f32 v[56:57], v[92:93], v[56:57]
	v_rcp_f32_e32 v92, v65
	v_and_b32_e32 v98, 0xffff0000, v62
	v_cvt_pk_bf16_f32 v48, v58, v48
	v_mul_f32_e32 v58, v60, v52
	v_and_b32_e32 v61, 0xffff0000, v49
	v_and_b32_e32 v60, 0xffff0000, v53
	v_mul_f32_e32 v62, 0xbfb8aa3b, v98
	v_pk_mul_f32 v[52:53], v[74:75], v[60:61]
	v_exp_f32_e32 v62, v62
	v_add_f32_e32 v49, v52, v53
	v_lshlrev_b32_e32 v53, 16, v50
	v_lshlrev_b32_e32 v52, 16, v54
	v_pk_mul_f32 v[52:53], v[74:75], v[52:53]
	v_pk_mul_f32 v[96:97], v[92:93], v[96:97]
	v_add_f32_e32 v52, v52, v53
	v_add_f32_e32 v49, v57, v49
	v_add_f32_e32 v52, v97, v52
	v_add_f32_e32 v62, 1.0, v62
	v_mul_f32_e32 v49, v56, v49
	v_mul_f32_e32 v56, v96, v52
	v_and_b32_e32 v53, 0xffff0000, v50
	v_and_b32_e32 v52, 0xffff0000, v54
	v_rcp_f32_e32 v92, v62
	v_pk_mul_f32 v[52:53], v[74:75], v[52:53]
	v_cvt_pk_bf16_f32 v49, v58, v49
	v_lshlrev_b32_e32 v57, 16, v51
	v_add_f32_e32 v50, v52, v53
	v_lshlrev_b32_e32 v52, 16, v63
	v_mul_f32_e32 v53, 0xbfb8aa3b, v52
	v_exp_f32_e32 v53, v53
	v_pk_mul_f32 v[98:99], v[92:93], v[98:99]
	v_and_b32_e32 v54, 0xffff0000, v63
	v_add_f32_e32 v50, v99, v50
	v_mul_f32_e32 v50, v98, v50
	v_cvt_pk_bf16_f32 v50, v56, v50
	v_add_f32_e32 v53, 1.0, v53
	v_lshlrev_b32_e32 v56, 16, v55
	v_rcp_f32_e32 v92, v53
	v_pk_mul_f32 v[56:57], v[74:75], v[56:57]
	v_lshlrev_b32_e32 v53, 16, v59
	v_add_f32_e32 v56, v56, v57
	v_mul_f32_e32 v57, 0xbfb8aa3b, v54
	v_exp_f32_e32 v57, v57
	v_pk_mul_f32 v[52:53], v[92:93], v[52:53]
	v_and_b32_e32 v62, 0xc0, v76
	v_add_f32_e32 v53, v53, v56
	v_mul_f32_e32 v56, v52, v53
	v_and_b32_e32 v53, 0xffff0000, v51
	v_add_f32_e32 v51, 1.0, v57
	v_rcp_f32_e32 v92, v51
	v_and_b32_e32 v52, 0xffff0000, v55
	v_pk_mul_f32 v[52:53], v[74:75], v[52:53]
	v_lshlrev_b32_e32 v194, 1, v62
	v_and_b32_e32 v55, 0xffff0000, v59
	v_add_f32_e32 v51, v52, v53
	v_lshl_add_u64 v[52:53], v[72:73], 0, v[194:195]
	v_mov_b32_e32 v65, v195
	v_pk_mul_f32 v[54:55], v[92:93], v[54:55]
	v_lshl_add_u64 v[52:53], v[52:53], 0, v[64:65]
	v_add_f32_e32 v51, v55, v51
	v_add_co_u32_e32 v52, vcc, 0xd000000, v52
	v_mul_f32_e32 v51, v54, v51
	s_nop 0
	v_addc_co_u32_e32 v53, vcc, 0, v53, vcc
	v_cvt_pk_bf16_f32 v51, v56, v51
	global_store_dwordx4 v[52:53], v[48:51], off offset:1024 sc1
	s_and_saveexec_b64 s[18:19], s[8:9]
	s_cbranch_execnz .LBB0_594
	s_or_b64 exec, exec, s[18:19]
	s_and_saveexec_b64 s[8:9], s[6:7]
	s_cbranch_execnz .LBB0_595

.LBB0_594:
	v_max3_f32 v50, v77, v80, v83
	v_sub_f32_e32 v48, v77, v50
	v_mul_f32_e32 v48, 0x3fb8aa3b, v48
	v_exp_f32_e32 v49, v48
	v_sub_f32_e32 v48, v80, v50
	v_sub_f32_e32 v50, v83, v50
	v_mul_f32_e32 v50, 0x3fb8aa3b, v50
	v_exp_f32_e32 v51, v50
	v_lshlrev_b32_e32 v50, 16, v20
	v_mul_f32_e32 v48, 0x3fb8aa3b, v48
	v_mul_f32_e32 v52, 0xbfb8aa3b, v50
	v_exp_f32_e32 v48, v48
	v_exp_f32_e32 v53, v52
	v_and_b32_e32 v56, 0xffff0000, v20
	v_lshlrev_b32_e32 v58, 16, v21
	v_add_f32_e32 v52, v49, v48
	v_add_f32_e32 v53, 1.0, v53
	v_add_f32_e32 v52, v51, v52
	v_rcp_f32_e32 v54, v53
	v_mul_f32_e32 v53, 0xbfb8aa3b, v56
	v_rcp_f32_e32 v52, v52
	v_exp_f32_e32 v53, v53
	v_and_b32_e32 v57, 0xffff0000, v4
	v_and_b32_e32 v60, 0xffff0000, v21
	v_mul_f32_e32 v55, v51, v52
	v_lshlrev_b32_e32 v51, 16, v4
	v_add_f32_e32 v53, 1.0, v53
	v_pk_mul_f32 v[50:51], v[54:55], v[50:51]
	v_rcp_f32_e32 v54, v53
	v_mul_f32_e32 v53, 0xbfb8aa3b, v58
	v_exp_f32_e32 v53, v53
	v_lshlrev_b32_e32 v59, 16, v5
	v_pk_mul_f32 v[56:57], v[54:55], v[56:57]
	v_lshlrev_b32_e32 v62, 16, v22
	v_add_f32_e32 v53, 1.0, v53
	v_rcp_f32_e32 v54, v53
	v_mul_f32_e32 v53, 0xbfb8aa3b, v60
	v_exp_f32_e32 v53, v53
	v_and_b32_e32 v61, 0xffff0000, v5
	v_pk_mul_f32 v[58:59], v[54:55], v[58:59]
	v_and_b32_e32 v72, 0xffff0000, v22
	v_add_f32_e32 v53, 1.0, v53
	v_rcp_f32_e32 v54, v53
	v_mul_f32_e32 v53, 0xbfb8aa3b, v62
	v_exp_f32_e32 v53, v53
	v_lshlrev_b32_e32 v63, 16, v6
	v_pk_mul_f32 v[60:61], v[54:55], v[60:61]
	v_and_b32_e32 v73, 0xffff0000, v6
	v_add_f32_e32 v53, 1.0, v53
	v_rcp_f32_e32 v54, v53
	v_mul_f32_e32 v53, 0xbfb8aa3b, v72
	v_exp_f32_e32 v53, v53
	v_pk_mul_f32 v[62:63], v[54:55], v[62:63]
	v_add_f32_e32 v53, 1.0, v53
	v_rcp_f32_e32 v54, v53
	v_pk_mul_f32 v[52:53], v[48:49], v[52:53] op_sel_hi:[1,0]
	v_lshlrev_b32_e32 v49, 16, v0
	v_lshlrev_b32_e32 v48, 16, v36
	v_pk_mul_f32 v[48:49], v[52:53], v[48:49]
	v_pk_mul_f32 v[72:73], v[54:55], v[72:73]
	v_add_f32_e32 v48, v48, v49
	v_add_f32_e32 v48, v51, v48
	v_mul_f32_e32 v50, v50, v48
	v_and_b32_e32 v49, 0xffff0000, v0
	v_and_b32_e32 v48, 0xffff0000, v36
	v_pk_mul_f32 v[48:49], v[52:53], v[48:49]
	v_lshlrev_b32_e32 v51, 16, v1
	v_add_f32_e32 v48, v48, v49
	v_add_f32_e32 v48, v57, v48
	v_mul_f32_e32 v48, v56, v48
	v_cvt_pk_bf16_f32 v48, v50, v48
	v_lshlrev_b32_e32 v50, 16, v37
	v_pk_mul_f32 v[50:51], v[52:53], v[50:51]
	v_lshlrev_b32_e32 v56, 16, v23
	v_add_f32_e32 v49, v50, v51
	v_and_b32_e32 v51, 0xffff0000, v1
	v_and_b32_e32 v50, 0xffff0000, v37
	v_pk_mul_f32 v[50:51], v[52:53], v[50:51]
	v_add_f32_e32 v49, v59, v49
	v_add_f32_e32 v50, v50, v51
	v_add_f32_e32 v50, v61, v50
	v_mul_f32_e32 v49, v58, v49
	v_mul_f32_e32 v50, v60, v50
	v_cvt_pk_bf16_f32 v49, v49, v50
	v_lshlrev_b32_e32 v51, 16, v2
	v_lshlrev_b32_e32 v50, 16, v38
	v_pk_mul_f32 v[50:51], v[52:53], v[50:51]
	v_lshlrev_b32_e32 v59, 16, v3
	v_add_f32_e32 v50, v50, v51
	v_add_f32_e32 v50, v63, v50
	v_mul_f32_e32 v54, v62, v50
	v_and_b32_e32 v51, 0xffff0000, v2
	v_and_b32_e32 v50, 0xffff0000, v38
	v_pk_mul_f32 v[50:51], v[52:53], v[50:51]
	v_lshlrev_b32_e32 v58, 16, v39
	v_add_f32_e32 v50, v50, v51
	v_mul_f32_e32 v51, 0xbfb8aa3b, v56
	v_exp_f32_e32 v51, v51
	v_add_f32_e32 v50, v73, v50
	v_mul_f32_e32 v50, v72, v50
	v_cvt_pk_bf16_f32 v50, v54, v50
	v_add_f32_e32 v51, 1.0, v51
	v_rcp_f32_e32 v54, v51
	v_pk_mul_f32 v[58:59], v[52:53], v[58:59]
	v_lshlrev_b32_e32 v57, 16, v7
	v_add_f32_e32 v51, v58, v59
	v_and_b32_e32 v58, 0xffff0000, v23
	v_pk_mul_f32 v[56:57], v[54:55], v[56:57]
	v_mul_f32_e32 v54, 0xbfb8aa3b, v58
	v_exp_f32_e32 v54, v54
	v_add_f32_e32 v51, v57, v51
	v_mul_f32_e32 v51, v56, v51
	v_and_b32_e32 v57, 0xffff0000, v3
	v_add_f32_e32 v54, 1.0, v54
	v_rcp_f32_e32 v54, v54
	v_and_b32_e32 v56, 0xffff0000, v39
	v_pk_mul_f32 v[52:53], v[52:53], v[56:57]
	v_and_b32_e32 v59, 0xffff0000, v7
	v_pk_mul_f32 v[54:55], v[54:55], v[58:59]
	v_add_f32_e32 v52, v52, v53
	v_add_f32_e32 v52, v55, v52
	v_mul_f32_e32 v52, v54, v52
	v_cvt_pk_bf16_f32 v51, v51, v52
	v_lshlrev_b64 v[52:53], 11, v[70:71]
	v_lshl_add_u64 v[52:53], s[0:1], 0, v[52:53]
	v_lshl_add_u64 v[52:53], v[52:53], 0, v[194:195]
	v_lshl_add_u64 v[52:53], v[52:53], 0, v[64:65]
	v_add_co_u32_e32 v52, vcc, 0xd000000, v52
	s_nop 1
	v_addc_co_u32_e32 v53, vcc, 0, v53, vcc
	global_store_dwordx4 v[52:53], v[48:51], off offset:1024 sc1
	s_or_b64 exec, exec, s[18:19]
	s_and_saveexec_b64 s[8:9], s[6:7]
	s_cbranch_execz .LBB0_593
.LBB0_595:
	v_max3_f32 v50, v79, v82, v85
	v_sub_f32_e32 v48, v79, v50
	v_mul_f32_e32 v48, 0x3fb8aa3b, v48
	v_exp_f32_e32 v49, v48
	v_sub_f32_e32 v48, v82, v50
	v_sub_f32_e32 v50, v85, v50
	v_mul_f32_e32 v50, 0x3fb8aa3b, v50
	v_exp_f32_e32 v51, v50
	v_lshlrev_b32_e32 v50, 16, v28
	v_mul_f32_e32 v48, 0x3fb8aa3b, v48
	v_mul_f32_e32 v52, 0xbfb8aa3b, v50
	v_exp_f32_e32 v48, v48
	v_exp_f32_e32 v53, v52
	v_and_b32_e32 v56, 0xffff0000, v28
	v_lshlrev_b32_e32 v58, 16, v29
	v_add_f32_e32 v52, v49, v48
	v_add_f32_e32 v53, 1.0, v53
	v_add_f32_e32 v52, v51, v52
	v_rcp_f32_e32 v54, v53
	v_mul_f32_e32 v53, 0xbfb8aa3b, v56
	v_rcp_f32_e32 v52, v52
	v_exp_f32_e32 v53, v53
	v_and_b32_e32 v57, 0xffff0000, v12
	v_and_b32_e32 v60, 0xffff0000, v29
	v_mul_f32_e32 v55, v51, v52
	v_lshlrev_b32_e32 v51, 16, v12
	v_add_f32_e32 v53, 1.0, v53
	v_pk_mul_f32 v[50:51], v[54:55], v[50:51]
	v_rcp_f32_e32 v54, v53
	v_mul_f32_e32 v53, 0xbfb8aa3b, v58
	v_exp_f32_e32 v53, v53
	v_lshlrev_b32_e32 v59, 16, v13
	v_pk_mul_f32 v[56:57], v[54:55], v[56:57]
	v_lshlrev_b32_e32 v62, 16, v30
	v_add_f32_e32 v53, 1.0, v53
	v_rcp_f32_e32 v54, v53
	v_mul_f32_e32 v53, 0xbfb8aa3b, v60
	v_exp_f32_e32 v53, v53
	v_and_b32_e32 v61, 0xffff0000, v13
	v_pk_mul_f32 v[58:59], v[54:55], v[58:59]
	v_and_b32_e32 v70, 0xffff0000, v30
	v_add_f32_e32 v53, 1.0, v53
	v_rcp_f32_e32 v54, v53
	v_mul_f32_e32 v53, 0xbfb8aa3b, v62
	v_exp_f32_e32 v53, v53
	v_lshlrev_b32_e32 v63, 16, v14
	v_pk_mul_f32 v[60:61], v[54:55], v[60:61]
	v_and_b32_e32 v71, 0xffff0000, v14
	v_add_f32_e32 v53, 1.0, v53
	v_rcp_f32_e32 v54, v53
	v_mul_f32_e32 v53, 0xbfb8aa3b, v70
	v_exp_f32_e32 v53, v53
	v_mov_b32_e32 v65, v195
	v_pk_mul_f32 v[62:63], v[54:55], v[62:63]
	v_add_f32_e32 v53, 1.0, v53
	v_rcp_f32_e32 v54, v53
	v_pk_mul_f32 v[52:53], v[48:49], v[52:53] op_sel_hi:[1,0]
	v_lshlrev_b32_e32 v49, 16, v16
	v_lshlrev_b32_e32 v48, 16, v40
	v_pk_mul_f32 v[48:49], v[52:53], v[48:49]
	v_pk_mul_f32 v[70:71], v[54:55], v[70:71]
	v_add_f32_e32 v48, v48, v49
	v_add_f32_e32 v48, v51, v48
	v_mul_f32_e32 v50, v50, v48
	v_and_b32_e32 v49, 0xffff0000, v16
	v_and_b32_e32 v48, 0xffff0000, v40
	v_pk_mul_f32 v[48:49], v[52:53], v[48:49]
	v_lshlrev_b32_e32 v51, 16, v17
	v_add_f32_e32 v48, v48, v49
	v_add_f32_e32 v48, v57, v48
	v_mul_f32_e32 v48, v56, v48
	v_cvt_pk_bf16_f32 v48, v50, v48
	v_lshlrev_b32_e32 v50, 16, v41
	v_pk_mul_f32 v[50:51], v[52:53], v[50:51]
	v_lshlrev_b32_e32 v56, 16, v31
	v_add_f32_e32 v49, v50, v51
	v_and_b32_e32 v51, 0xffff0000, v17
	v_and_b32_e32 v50, 0xffff0000, v41
	v_pk_mul_f32 v[50:51], v[52:53], v[50:51]
	v_add_f32_e32 v49, v59, v49
	v_add_f32_e32 v50, v50, v51
	v_add_f32_e32 v50, v61, v50
	v_mul_f32_e32 v49, v58, v49
	v_mul_f32_e32 v50, v60, v50
	v_cvt_pk_bf16_f32 v49, v49, v50
	v_lshlrev_b32_e32 v51, 16, v18
	v_lshlrev_b32_e32 v50, 16, v42
	v_pk_mul_f32 v[50:51], v[52:53], v[50:51]
	v_lshlrev_b32_e32 v59, 16, v19
	v_add_f32_e32 v50, v50, v51
	v_add_f32_e32 v50, v63, v50
	v_mul_f32_e32 v54, v62, v50
	v_and_b32_e32 v51, 0xffff0000, v18
	v_and_b32_e32 v50, 0xffff0000, v42
	v_pk_mul_f32 v[50:51], v[52:53], v[50:51]
	v_lshlrev_b32_e32 v58, 16, v43
	v_add_f32_e32 v50, v50, v51
	v_mul_f32_e32 v51, 0xbfb8aa3b, v56
	v_exp_f32_e32 v51, v51
	v_add_f32_e32 v50, v71, v50
	v_mul_f32_e32 v50, v70, v50
	v_cvt_pk_bf16_f32 v50, v54, v50
	v_add_f32_e32 v51, 1.0, v51
	v_rcp_f32_e32 v54, v51
	v_pk_mul_f32 v[58:59], v[52:53], v[58:59]
	v_lshlrev_b32_e32 v57, 16, v15
	v_add_f32_e32 v51, v58, v59
	v_and_b32_e32 v58, 0xffff0000, v31
	v_pk_mul_f32 v[56:57], v[54:55], v[56:57]
	v_mul_f32_e32 v54, 0xbfb8aa3b, v58
	v_exp_f32_e32 v54, v54
	v_add_f32_e32 v51, v57, v51
	v_mul_f32_e32 v51, v56, v51
	v_and_b32_e32 v57, 0xffff0000, v19
	v_add_f32_e32 v54, 1.0, v54
	v_rcp_f32_e32 v54, v54
	v_and_b32_e32 v56, 0xffff0000, v43
	v_pk_mul_f32 v[52:53], v[52:53], v[56:57]
	v_and_b32_e32 v59, 0xffff0000, v15
	v_pk_mul_f32 v[54:55], v[54:55], v[58:59]
	v_add_f32_e32 v52, v52, v53
	v_add_f32_e32 v52, v55, v52
	v_mul_f32_e32 v52, v54, v52
	v_cvt_pk_bf16_f32 v51, v51, v52
	v_lshlrev_b64 v[52:53], 11, v[68:69]
	v_lshl_add_u64 v[52:53], s[0:1], 0, v[52:53]
	v_lshl_add_u64 v[52:53], v[52:53], 0, v[194:195]
	v_lshl_add_u64 v[52:53], v[52:53], 0, v[64:65]
	v_add_co_u32_e32 v52, vcc, 0xd000000, v52
	s_nop 1
	v_addc_co_u32_e32 v53, vcc, 0, v53, vcc
	global_store_dwordx4 v[52:53], v[48:51], off offset:1024 sc1
	s_or_b64 exec, exec, s[8:9]
	s_and_saveexec_b64 s[6:7], s[4:5]
	s_cbranch_execz .LBB0_584
.LBB0_596:
	v_max3_f32 v50, v78, v81, v84
	v_sub_f32_e32 v48, v78, v50
	v_sub_f32_e32 v49, v81, v50
	v_sub_f32_e32 v50, v84, v50
	v_mul_f32_e32 v50, 0x3fb8aa3b, v50
	v_exp_f32_e32 v51, v50
	v_lshlrev_b32_e32 v50, 16, v24
	v_mul_f32_e32 v48, 0x3fb8aa3b, v48
	v_mul_f32_e32 v49, 0x3fb8aa3b, v49
	v_mul_f32_e32 v52, 0xbfb8aa3b, v50
	v_exp_f32_e32 v48, v48
	v_exp_f32_e32 v49, v49
	v_exp_f32_e32 v53, v52
	v_and_b32_e32 v56, 0xffff0000, v24
	v_lshlrev_b32_e32 v58, 16, v25
	v_add_f32_e32 v52, v48, v49
	v_add_f32_e32 v53, 1.0, v53
	v_add_f32_e32 v52, v51, v52
	v_rcp_f32_e32 v54, v53
	v_mul_f32_e32 v53, 0xbfb8aa3b, v56
	v_rcp_f32_e32 v52, v52
	v_exp_f32_e32 v53, v53
	v_and_b32_e32 v57, 0xffff0000, v8
	v_and_b32_e32 v60, 0xffff0000, v25
	v_mul_f32_e32 v55, v51, v52
	v_lshlrev_b32_e32 v51, 16, v8
	v_add_f32_e32 v53, 1.0, v53
	v_pk_mul_f32 v[50:51], v[54:55], v[50:51]
	v_rcp_f32_e32 v54, v53
	v_mul_f32_e32 v53, 0xbfb8aa3b, v58
	v_exp_f32_e32 v53, v53
	v_lshlrev_b32_e32 v59, 16, v9
	v_pk_mul_f32 v[56:57], v[54:55], v[56:57]
	v_lshlrev_b32_e32 v62, 16, v26
	v_add_f32_e32 v53, 1.0, v53
	v_rcp_f32_e32 v54, v53
	v_mul_f32_e32 v53, 0xbfb8aa3b, v60
	v_exp_f32_e32 v53, v53
	v_and_b32_e32 v61, 0xffff0000, v9
	v_pk_mul_f32 v[58:59], v[54:55], v[58:59]
	v_and_b32_e32 v68, 0xffff0000, v26
	v_add_f32_e32 v53, 1.0, v53
	v_rcp_f32_e32 v54, v53
	v_mul_f32_e32 v53, 0xbfb8aa3b, v62
	v_exp_f32_e32 v53, v53
	v_lshlrev_b32_e32 v63, 16, v10
	v_pk_mul_f32 v[60:61], v[54:55], v[60:61]
	v_and_b32_e32 v69, 0xffff0000, v10
	v_add_f32_e32 v53, 1.0, v53
	v_rcp_f32_e32 v54, v53
	v_mul_f32_e32 v53, 0xbfb8aa3b, v68
	v_exp_f32_e32 v53, v53
	v_mov_b32_e32 v65, v195
	v_pk_mul_f32 v[62:63], v[54:55], v[62:63]
	v_add_f32_e32 v53, 1.0, v53
	v_rcp_f32_e32 v54, v53
	v_pk_mul_f32 v[52:53], v[48:49], v[52:53] op_sel_hi:[1,0]
	v_lshlrev_b32_e32 v49, 16, v44
	v_lshlrev_b32_e32 v48, 16, v32
	v_pk_mul_f32 v[48:49], v[52:53], v[48:49]
	v_pk_mul_f32 v[68:69], v[54:55], v[68:69]
	v_add_f32_e32 v48, v48, v49
	v_add_f32_e32 v48, v51, v48
	v_mul_f32_e32 v50, v50, v48
	v_and_b32_e32 v49, 0xffff0000, v44
	v_and_b32_e32 v48, 0xffff0000, v32
	v_pk_mul_f32 v[48:49], v[52:53], v[48:49]
	v_lshlrev_b32_e32 v51, 16, v45
	v_add_f32_e32 v48, v48, v49
	v_add_f32_e32 v48, v57, v48
	v_mul_f32_e32 v48, v56, v48
	v_cvt_pk_bf16_f32 v48, v50, v48
	v_lshlrev_b32_e32 v50, 16, v33
	v_pk_mul_f32 v[50:51], v[52:53], v[50:51]
	v_lshlrev_b32_e32 v56, 16, v27
	v_add_f32_e32 v49, v50, v51
	v_and_b32_e32 v51, 0xffff0000, v45
	v_and_b32_e32 v50, 0xffff0000, v33
	v_pk_mul_f32 v[50:51], v[52:53], v[50:51]
	v_add_f32_e32 v49, v59, v49
	v_add_f32_e32 v50, v50, v51
	v_add_f32_e32 v50, v61, v50
	v_mul_f32_e32 v49, v58, v49
	v_mul_f32_e32 v50, v60, v50
	v_cvt_pk_bf16_f32 v49, v49, v50
	v_lshlrev_b32_e32 v51, 16, v46
	v_lshlrev_b32_e32 v50, 16, v34
	v_pk_mul_f32 v[50:51], v[52:53], v[50:51]
	v_lshlrev_b32_e32 v59, 16, v47
	v_add_f32_e32 v50, v50, v51
	v_add_f32_e32 v50, v63, v50
	v_mul_f32_e32 v54, v62, v50
	v_and_b32_e32 v51, 0xffff0000, v46
	v_and_b32_e32 v50, 0xffff0000, v34
	v_pk_mul_f32 v[50:51], v[52:53], v[50:51]
	v_lshlrev_b32_e32 v58, 16, v35
	v_add_f32_e32 v50, v50, v51
	v_mul_f32_e32 v51, 0xbfb8aa3b, v56
	v_exp_f32_e32 v51, v51
	v_add_f32_e32 v50, v69, v50
	v_mul_f32_e32 v50, v68, v50
	v_cvt_pk_bf16_f32 v50, v54, v50
	v_add_f32_e32 v51, 1.0, v51
	v_rcp_f32_e32 v54, v51
	v_pk_mul_f32 v[58:59], v[52:53], v[58:59]
	v_lshlrev_b32_e32 v57, 16, v11
	v_add_f32_e32 v51, v58, v59
	v_and_b32_e32 v58, 0xffff0000, v27
	v_pk_mul_f32 v[56:57], v[54:55], v[56:57]
	v_mul_f32_e32 v54, 0xbfb8aa3b, v58
	v_exp_f32_e32 v54, v54
	v_add_f32_e32 v51, v57, v51
	v_mul_f32_e32 v51, v56, v51
	v_and_b32_e32 v57, 0xffff0000, v47
	v_add_f32_e32 v54, 1.0, v54
	v_rcp_f32_e32 v54, v54
	v_and_b32_e32 v56, 0xffff0000, v35
	v_pk_mul_f32 v[52:53], v[52:53], v[56:57]
	v_and_b32_e32 v59, 0xffff0000, v11
	v_pk_mul_f32 v[54:55], v[54:55], v[58:59]
	v_add_f32_e32 v52, v52, v53
	v_add_f32_e32 v52, v55, v52
	v_mul_f32_e32 v52, v54, v52
	v_cvt_pk_bf16_f32 v51, v51, v52
	v_lshlrev_b64 v[52:53], 11, v[66:67]
	v_lshl_add_u64 v[52:53], s[0:1], 0, v[52:53]
	v_lshl_add_u64 v[52:53], v[52:53], 0, v[194:195]
	v_lshl_add_u64 v[52:53], v[52:53], 0, v[64:65]
	v_add_co_u32_e32 v52, vcc, 0xd000000, v52
	s_nop 1
	v_addc_co_u32_e32 v53, vcc, 0, v53, vcc
	global_store_dwordx4 v[52:53], v[48:51], off offset:1024 sc1
	s_branch .LBB0_584

.LBB0_641:
	s_andn2_saveexec_b64 s[6:7], s[6:7]
	s_cbranch_execz .LBB0_661
	s_mov_b64 s[6:7], exec
	s_waitcnt lgkmcnt(0)
	s_waitcnt vmcnt(0)
	v_mbcnt_lo_u32_b32 v1, s6, 0
	v_mbcnt_hi_u32_b32 v1, s7, v1
	v_cmp_eq_u32_e32 vcc, 0, v1
	s_and_saveexec_b64 s[8:9], vcc
	s_cbranch_execz .LBB0_644
	s_bcnt1_i32_b64 s3, s[6:7]
	v_mov_b32_e32 v2, s3
	global_atomic_add v2, v220, v2, s[4:5] offset:1024 sc0
